# weight conversion: while a tile's loads are in flight, touch the same source rows of the block's next tile (ffn_in, w_out) so its loads hit L2
# speedup vs baseline: 1.0179x; 1.0016x over previous
; DEVI int srccol_ffn(int n) { return ((n >> 7) & 1) * FFN_H + (n >> 8) * 128 + (n & 127); }
; DEVI void conv_tile(unsigned char* smem, const float* src, int ldsrc, int K, bf16_t* dst, int mode, int ntile, int ktile) {
;     ...
;     const int n = n0 + tx;
;     const int sc = mode == 0 ? srccol_win(n) : (mode == 1 ? srccol_ffn(n) : n);
; #pragma unroll
;     for (int i = 0; i < 8; ++i) {
;         const int kk = ty + 8 * i;
;         tile[kk * 65 + tx] = sc >= 0 ? src[(size_t)(k0 + kk) * ldsrc + sc] : 0.0f;
;     }
;     __syncthreads();
;     const int nr = tid >> 3, ks = (tid & 7) * 8;
;     float v[8];
; #pragma unroll
;     for (int j = 0; j < 8; ++j) v[j] = tile[(ks + j) * 65 + nr];
;     u32x4 w; w.x = cvt_pk_bf16(v[0], v[1]); w.y = cvt_pk_bf16(v[2], v[3]); w.z = cvt_pk_bf16(v[4], v[5]); w.w = cvt_pk_bf16(v[6], v[7]);
;     *(u32x4*)(dst + (size_t)(n0 + nr) * K + k0 + ks) = w;
;     __syncthreads();
.LBB0_47:
	s_andn2_b64 vcc, exec, s[4:5]
	s_cbranch_vccnz .LBB0_49
	s_add_i32 s0, s18, 0xffffd980
	s_bfe_i32 s4, s18, 0x10006
	s_add_i32 s2, s9, 0xffffb300
	s_and_b32 s4, s4, 0x1600
	s_and_b32 s0, s0, 0xffffff80
	v_mov_b32_e32 v1, v199
	s_add_i32 s4, s4, s0
	s_and_b32 s0, s2, 64
	s_or_b32 s0, s4, s0
	v_and_b32_e32 v20, 63, v1
	v_readlane_b32 s36, v252, 38
	v_ashrrev_i32_e32 v21, 6, v1
	s_and_b32 s6, s3, 0x7c0
	v_or_b32_e32 v2, s0, v20
	v_readlane_b32 s48, v252, 50
	v_readlane_b32 s49, v252, 51
	s_and_b32 s2, s2, 0x7fffffc0
	s_lshl_b32 s0, s6, 1
	v_lshl_add_u64 v[4:5], v[2:3], 2, s[48:49]
	v_add_u32_e32 v2, s6, v21
	v_add_u32_e32 v8, 8, v2
	v_add_u32_e32 v10, 16, v2
	v_add_u32_e32 v12, 24, v2
	v_mad_i64_i32 v[6:7], s[4:5], v2, s16, v[4:5]
	v_mad_i64_i32 v[8:9], s[4:5], v8, s16, v[4:5]
	v_mad_i64_i32 v[10:11], s[4:5], v10, s16, v[4:5]
	v_mad_i64_i32 v[12:13], s[4:5], v12, s16, v[4:5]
	v_add_u32_e32 v14, 32, v2
	v_add_u32_e32 v16, 40, v2
	v_add_u32_e32 v18, 48, v2
	v_add_u32_e32 v2, 56, v2
	v_mad_i64_i32 v[14:15], s[4:5], v14, s16, v[4:5]
	v_mad_i64_i32 v[16:17], s[4:5], v16, s16, v[4:5]
	v_mad_i64_i32 v[18:19], s[4:5], v18, s16, v[4:5]
	v_mad_i64_i32 v[4:5], s[4:5], v2, s16, v[4:5]
	v_mov_b64_e32 v[228:229], v[6:7]
	v_mov_b64_e32 v[230:231], v[8:9]
	v_mov_b64_e32 v[232:233], v[10:11]
	v_mov_b64_e32 v[234:235], v[12:13]
	v_mov_b64_e32 v[236:237], v[14:15]
	v_mov_b64_e32 v[238:239], v[16:17]
	v_mov_b64_e32 v[240:241], v[18:19]
	v_mov_b64_e32 v[242:243], v[4:5]
	global_load_dword v6, v[6:7], off
	s_nop 0
	global_load_dword v7, v[8:9], off
	s_nop 0
	global_load_dword v8, v[10:11], off
	global_load_dword v9, v[12:13], off
	s_nop 0
	global_load_dword v10, v[14:15], off
	global_load_dword v11, v[16:17], off
	global_load_dword v12, v[18:19], off
	global_load_dword v13, v[4:5], off
	s_add_i32 s101, s18, s90
	s_cmp_lt_u32 s101, 0x3c80
	s_cbranch_scc0 .Lcvt_nt_ffninA
	global_load_dword v244, v[228:229], off offset:1024
	global_load_dword v244, v[230:231], off offset:1024
	global_load_dword v244, v[232:233], off offset:1024
	global_load_dword v244, v[234:235], off offset:1024
	global_load_dword v244, v[236:237], off offset:1024
	global_load_dword v244, v[238:239], off offset:1024
	global_load_dword v244, v[240:241], off offset:1024
	global_load_dword v244, v[242:243], off offset:1024
	s_branch .Lcvt_j_ffninA
.Lcvt_nt_ffninA:
	global_load_dword v244, v[228:229], off
	global_load_dword v244, v[230:231], off
	global_load_dword v244, v[232:233], off
	global_load_dword v244, v[234:235], off
	global_load_dword v244, v[236:237], off
	global_load_dword v244, v[238:239], off
	global_load_dword v244, v[240:241], off
	global_load_dword v244, v[242:243], off
.Lcvt_j_ffninA:
	v_ashrrev_i32_e32 v2, 3, v1
	v_lshlrev_b32_e32 v1, 3, v1
	v_and_b32_e32 v1, 56, v1
	v_lshlrev_b32_e32 v5, 2, v20
	v_mul_lo_u32 v14, v21, s15
	v_lshlrev_b32_e32 v15, 2, v2
	v_add_u32_e32 v4, s2, v2
	v_mul_u32_u24_e32 v2, 0x104, v1
	v_add3_u32 v14, 0, v5, v14
	v_add3_u32 v15, 0, v15, v2
	v_lshlrev_b32_e32 v2, 1, v1
	v_add_u32_e32 v1, 0x400, v15
	v_ashrrev_i32_e32 v5, 31, v4
	v_readlane_b32 s4, v253, 30
	v_lshlrev_b64 v[4:5], 12, v[4:5]
	v_readlane_b32 s5, v253, 31
	v_readlane_b32 s37, v252, 39
	v_readlane_b32 s38, v252, 40
	v_lshl_add_u64 v[4:5], s[4:5], 0, v[4:5]
	v_lshl_add_u64 v[4:5], v[4:5], 0, s[0:1]
	v_readlane_b32 s39, v252, 41
	v_readlane_b32 s40, v252, 42
	v_readlane_b32 s41, v252, 43
	v_readlane_b32 s42, v252, 44
	v_readlane_b32 s43, v252, 45
	v_readlane_b32 s44, v252, 46
	v_readlane_b32 s45, v252, 47
	v_readlane_b32 s46, v252, 48
	v_readlane_b32 s47, v252, 49
	v_readlane_b32 s50, v252, 52
	v_readlane_b32 s51, v252, 53
	s_waitcnt vmcnt(15)
	ds_write_b32 v14, v6
	s_waitcnt vmcnt(14)
	ds_write_b32 v14, v7 offset:2080
	s_waitcnt vmcnt(13)
	ds_write_b32 v14, v8 offset:4160
	s_waitcnt vmcnt(12)
	ds_write_b32 v14, v9 offset:6240
	s_waitcnt vmcnt(11)
	ds_write_b32 v14, v10 offset:8320
	s_waitcnt vmcnt(10)
	ds_write_b32 v14, v11 offset:10400
	s_waitcnt vmcnt(9)
	ds_write_b32 v14, v12 offset:12480
	s_waitcnt vmcnt(8)
	ds_write_b32 v14, v13 offset:14560
	s_waitcnt lgkmcnt(0)
	s_barrier
	ds_read2_b32 v[6:7], v15 offset1:65
	ds_read2_b32 v[8:9], v15 offset0:130 offset1:195
	ds_read2_b32 v[10:11], v1 offset0:4 offset1:69
	ds_read2_b32 v[12:13], v1 offset0:134 offset1:199
	v_lshl_add_u64 v[14:15], v[4:5], 0, v[2:3]
	s_waitcnt lgkmcnt(3)
	v_cvt_pk_bf16_f32 v4, v6, v7
	s_waitcnt lgkmcnt(2)
	v_cvt_pk_bf16_f32 v5, v8, v9
	s_waitcnt lgkmcnt(1)
	v_cvt_pk_bf16_f32 v6, v10, v11
	s_waitcnt lgkmcnt(0)
	v_cvt_pk_bf16_f32 v7, v12, v13
	global_store_dwordx4 v[14:15], v[4:7], off
	s_barrier

; DEVI int srccol_ffn(int n) { return ((n >> 7) & 1) * FFN_H + (n >> 8) * 128 + (n & 127); }
; DEVI void conv_tile(unsigned char* smem, const float* src, int ldsrc, int K, bf16_t* dst, int mode, int ntile, int ktile) {
;     ...
;     const int n = n0 + tx;
;     const int sc = mode == 0 ? srccol_win(n) : (mode == 1 ? srccol_ffn(n) : n);
; #pragma unroll
;     for (int i = 0; i < 8; ++i) {
;         const int kk = ty + 8 * i;
;         tile[kk * 65 + tx] = sc >= 0 ? src[(size_t)(k0 + kk) * ldsrc + sc] : 0.0f;
.LBB0_50:
	s_andn2_b64 vcc, exec, s[4:5]
	s_cbranch_vccnz .LBB0_52
	v_mov_b32_e32 v1, v199
	s_and_b32 s0, s9, 0x7fc0
	s_add_i32 s2, s0, 0xffffbb00
	v_ashrrev_i32_e32 v23, 6, v1
	s_and_b32 s0, s3, 0x7c0
	v_add_u32_e32 v6, s0, v23
	v_and_b32_e32 v22, 63, v1
	v_readlane_b32 s36, v252, 38
	v_ashrrev_i32_e32 v7, 31, v6
	v_add_u32_e32 v10, 8, v6
	v_add_u32_e32 v12, 16, v6
	v_or_b32_e32 v2, s2, v22
	v_readlane_b32 s44, v252, 46
	v_readlane_b32 s45, v252, 47
	v_lshlrev_b64 v[8:9], 13, v[6:7]
	v_ashrrev_i32_e32 v11, 31, v10
	v_ashrrev_i32_e32 v13, 31, v12
	v_add_u32_e32 v14, 24, v6
	v_add_u32_e32 v16, 32, v6
	v_add_u32_e32 v18, 40, v6
	v_add_u32_e32 v20, 48, v6
	v_add_u32_e32 v6, 56, v6
	v_lshl_add_u64 v[4:5], v[2:3], 2, s[44:45]
	v_lshlrev_b64 v[10:11], 13, v[10:11]
	v_lshlrev_b64 v[12:13], 13, v[12:13]
	v_ashrrev_i32_e32 v15, 31, v14
	v_ashrrev_i32_e32 v17, 31, v16
	v_ashrrev_i32_e32 v19, 31, v18
	v_ashrrev_i32_e32 v21, 31, v20
	v_ashrrev_i32_e32 v7, 31, v6
	v_lshl_add_u64 v[8:9], v[4:5], 0, v[8:9]
	v_lshl_add_u64 v[10:11], v[4:5], 0, v[10:11]
	v_lshl_add_u64 v[12:13], v[4:5], 0, v[12:13]
	v_lshlrev_b64 v[14:15], 13, v[14:15]
	v_lshlrev_b64 v[16:17], 13, v[16:17]
	v_lshlrev_b64 v[18:19], 13, v[18:19]
	v_lshlrev_b64 v[20:21], 13, v[20:21]
	v_lshlrev_b64 v[6:7], 13, v[6:7]
	v_lshl_add_u64 v[14:15], v[4:5], 0, v[14:15]
	v_lshl_add_u64 v[16:17], v[4:5], 0, v[16:17]
	v_lshl_add_u64 v[18:19], v[4:5], 0, v[18:19]
	v_lshl_add_u64 v[20:21], v[4:5], 0, v[20:21]
	v_lshl_add_u64 v[4:5], v[4:5], 0, v[6:7]
	v_mov_b64_e32 v[228:229], v[8:9]
	v_mov_b64_e32 v[230:231], v[10:11]
	v_mov_b64_e32 v[232:233], v[12:13]
	v_mov_b64_e32 v[234:235], v[14:15]
	v_mov_b64_e32 v[236:237], v[16:17]
	v_mov_b64_e32 v[238:239], v[18:19]
	v_mov_b64_e32 v[240:241], v[20:21]
	v_mov_b64_e32 v[242:243], v[4:5]
	global_load_dword v6, v[8:9], off
	global_load_dword v7, v[10:11], off
	s_nop 0
	global_load_dword v8, v[12:13], off
	global_load_dword v9, v[14:15], off
	global_load_dword v10, v[16:17], off
	global_load_dword v11, v[18:19], off
	s_nop 0
	global_load_dword v12, v[20:21], off
	global_load_dword v13, v[4:5], off
	s_add_i32 s101, s18, s90
	s_cmp_lt_u32 s101, 0x2680
	s_cbranch_scc0 .Lcvt_nt_woutA
	global_load_dword v244, v[228:229], off offset:2048
	global_load_dword v244, v[230:231], off offset:2048
	global_load_dword v244, v[232:233], off offset:2048
	global_load_dword v244, v[234:235], off offset:2048
	global_load_dword v244, v[236:237], off offset:2048
	global_load_dword v244, v[238:239], off offset:2048
	global_load_dword v244, v[240:241], off offset:2048
	global_load_dword v244, v[242:243], off offset:2048
	s_branch .Lcvt_j_woutA

; DEVI void conv_tile(unsigned char* smem, const float* src, int ldsrc, int K, bf16_t* dst, int mode, int ntile, int ktile) {
;     ...
;         tile[kk * 65 + tx] = sc >= 0 ? src[(size_t)(k0 + kk) * ldsrc + sc] : 0.0f;
;     }
;     __syncthreads();
;     const int nr = tid >> 3, ks = (tid & 7) * 8;
;     float v[8];
; #pragma unroll
;     for (int j = 0; j < 8; ++j) v[j] = tile[(ks + j) * 65 + nr];
;     u32x4 w; w.x = cvt_pk_bf16(v[0], v[1]); w.y = cvt_pk_bf16(v[2], v[3]); w.z = cvt_pk_bf16(v[4], v[5]); w.w = cvt_pk_bf16(v[6], v[7]);
;     *(u32x4*)(dst + (size_t)(n0 + nr) * K + k0 + ks) = w;
;     __syncthreads();
.Lcvt_j_woutA:
	v_ashrrev_i32_e32 v2, 3, v1
	v_lshlrev_b32_e32 v1, 3, v1
	v_and_b32_e32 v1, 56, v1
	v_lshlrev_b32_e32 v5, 2, v22
	v_mul_lo_u32 v14, v23, s15
	v_lshlrev_b32_e32 v15, 2, v2
	v_mul_u32_u24_e32 v16, 0x104, v1
	v_add_u32_e32 v4, s2, v2
	v_add3_u32 v14, 0, v5, v14
	v_lshlrev_b32_e32 v2, 1, v1
	v_add3_u32 v1, 0, v15, v16
	v_add_u32_e32 v15, 0x400, v1
	v_ashrrev_i32_e32 v5, 31, v4
	v_readlane_b32 s4, v253, 32
	v_lshlrev_b64 v[4:5], 12, v[4:5]
	v_readlane_b32 s5, v253, 33
	s_lshl_b32 s0, s0, 1
	v_readlane_b32 s37, v252, 39
	v_lshl_add_u64 v[4:5], s[4:5], 0, v[4:5]
	v_lshl_add_u64 v[4:5], v[4:5], 0, s[0:1]
	v_readlane_b32 s38, v252, 40
	v_readlane_b32 s39, v252, 41
	v_readlane_b32 s40, v252, 42
	v_readlane_b32 s41, v252, 43
	v_readlane_b32 s42, v252, 44
	v_readlane_b32 s43, v252, 45
	v_readlane_b32 s46, v252, 48
	v_readlane_b32 s47, v252, 49
	v_readlane_b32 s48, v252, 50
	v_readlane_b32 s49, v252, 51
	v_readlane_b32 s50, v252, 52
	v_readlane_b32 s51, v252, 53
	s_waitcnt vmcnt(15)
	ds_write_b32 v14, v6
	s_waitcnt vmcnt(14)
	ds_write_b32 v14, v7 offset:2080
	s_waitcnt vmcnt(13)
	ds_write_b32 v14, v8 offset:4160
	s_waitcnt vmcnt(12)
	ds_write_b32 v14, v9 offset:6240
	s_waitcnt vmcnt(11)
	ds_write_b32 v14, v10 offset:8320
	s_waitcnt vmcnt(10)
	ds_write_b32 v14, v11 offset:10400
	s_waitcnt vmcnt(9)
	ds_write_b32 v14, v12 offset:12480
	s_waitcnt vmcnt(8)
	ds_write_b32 v14, v13 offset:14560
	s_waitcnt lgkmcnt(0)
	s_barrier
	ds_read2_b32 v[6:7], v1 offset1:65
	ds_read2_b32 v[8:9], v1 offset0:130 offset1:195
	ds_read2_b32 v[10:11], v15 offset0:4 offset1:69
	ds_read2_b32 v[12:13], v15 offset0:134 offset1:199
	v_lshl_add_u64 v[14:15], v[4:5], 0, v[2:3]
	s_waitcnt lgkmcnt(3)
	v_cvt_pk_bf16_f32 v4, v6, v7
	s_waitcnt lgkmcnt(2)
	v_cvt_pk_bf16_f32 v5, v8, v9
	s_waitcnt lgkmcnt(1)
	v_cvt_pk_bf16_f32 v6, v10, v11
	s_waitcnt lgkmcnt(0)
	v_cvt_pk_bf16_f32 v7, v12, v13
	global_store_dwordx4 v[14:15], v[4:7], off
	s_barrier

; DEVI int srccol_ffn(int n) { return ((n >> 7) & 1) * FFN_H + (n >> 8) * 128 + (n & 127); }
; DEVI void conv_tile(unsigned char* smem, const float* src, int ldsrc, int K, bf16_t* dst, int mode, int ntile, int ktile) {
;     ...
;     const int n = n0 + tx;
;     const int sc = mode == 0 ? srccol_win(n) : (mode == 1 ? srccol_ffn(n) : n);
; #pragma unroll
;     for (int i = 0; i < 8; ++i) {
;         const int kk = ty + 8 * i;
;         tile[kk * 65 + tx] = sc >= 0 ? src[(size_t)(k0 + kk) * ldsrc + sc] : 0.0f;
.LBB0_144:
	s_andn2_b64 vcc, exec, s[0:1]
	s_cbranch_vccnz .LBB0_146
	s_add_i32 s0, s15, 0xffffd980
	s_bfe_i32 s1, s15, 0x10006
	s_add_i32 s2, s13, 0xffffb300
	s_and_b32 s1, s1, 0x1600
	s_and_b32 s0, s0, 0xffffff80
	v_mov_b32_e32 v16, v199
	s_add_i32 s1, s1, s0
	s_and_b32 s0, s2, 64
	s_or_b32 s0, s1, s0
	v_and_b32_e32 v17, 63, v16
	v_ashrrev_i32_e32 v18, 6, v16
	s_and_b32 s3, s14, 0x7c0
	v_or_b32_e32 v148, s0, v17
	v_readlane_b32 s0, v252, 62
	v_readlane_b32 s1, v252, 63
	v_add_u32_e32 v19, s3, v18
	s_mov_b32 s6, 0xb000
	v_lshl_add_u64 v[0:1], v[148:149], 2, s[0:1]
	v_add_u32_e32 v4, 8, v19
	v_add_u32_e32 v6, 16, v19
	v_add_u32_e32 v8, 24, v19
	v_mad_i64_i32 v[2:3], s[0:1], v19, s6, v[0:1]
	v_mad_i64_i32 v[4:5], s[0:1], v4, s6, v[0:1]
	v_mad_i64_i32 v[6:7], s[0:1], v6, s6, v[0:1]
	v_mad_i64_i32 v[8:9], s[0:1], v8, s6, v[0:1]
	v_add_u32_e32 v10, 32, v19
	v_add_u32_e32 v12, 40, v19
	v_add_u32_e32 v14, 48, v19
	v_add_u32_e32 v19, 56, v19
	v_mad_i64_i32 v[10:11], s[0:1], v10, s6, v[0:1]
	v_mad_i64_i32 v[12:13], s[0:1], v12, s6, v[0:1]
	v_mad_i64_i32 v[14:15], s[0:1], v14, s6, v[0:1]
	v_mad_i64_i32 v[0:1], s[0:1], v19, s6, v[0:1]
	v_mov_b64_e32 v[228:229], v[2:3]
	v_mov_b64_e32 v[230:231], v[4:5]
	v_mov_b64_e32 v[232:233], v[6:7]
	v_mov_b64_e32 v[234:235], v[8:9]
	v_mov_b64_e32 v[236:237], v[10:11]
	v_mov_b64_e32 v[238:239], v[12:13]
	v_mov_b64_e32 v[240:241], v[14:15]
	v_mov_b64_e32 v[242:243], v[0:1]
	global_load_dword v2, v[2:3], off
	s_nop 0
	global_load_dword v3, v[4:5], off
	s_nop 0
	global_load_dword v4, v[6:7], off
	global_load_dword v5, v[8:9], off
	s_nop 0
	global_load_dword v6, v[10:11], off
	global_load_dword v7, v[12:13], off
	global_load_dword v8, v[14:15], off
	global_load_dword v9, v[0:1], off
	s_add_i32 s101, s15, s90
	s_cmp_lt_u32 s101, 0x3c80
	s_cbranch_scc0 .Lcvt_nt_ffninB
	global_load_dword v244, v[228:229], off offset:1024
	global_load_dword v244, v[230:231], off offset:1024
	global_load_dword v244, v[232:233], off offset:1024
	global_load_dword v244, v[234:235], off offset:1024
	global_load_dword v244, v[236:237], off offset:1024
	global_load_dword v244, v[238:239], off offset:1024
	global_load_dword v244, v[240:241], off offset:1024
	global_load_dword v244, v[242:243], off offset:1024
	s_branch .Lcvt_j_ffninB

; DEVI void conv_tile(unsigned char* smem, const float* src, int ldsrc, int K, bf16_t* dst, int mode, int ntile, int ktile) {
;     ...
;         tile[kk * 65 + tx] = sc >= 0 ? src[(size_t)(k0 + kk) * ldsrc + sc] : 0.0f;
;     }
;     __syncthreads();
;     const int nr = tid >> 3, ks = (tid & 7) * 8;
;     float v[8];
; #pragma unroll
;     for (int j = 0; j < 8; ++j) v[j] = tile[(ks + j) * 65 + nr];
;     u32x4 w; w.x = cvt_pk_bf16(v[0], v[1]); w.y = cvt_pk_bf16(v[2], v[3]); w.z = cvt_pk_bf16(v[4], v[5]); w.w = cvt_pk_bf16(v[6], v[7]);
;     *(u32x4*)(dst + (size_t)(n0 + nr) * K + k0 + ks) = w;
;     __syncthreads();
.Lcvt_j_ffninB:
	v_lshlrev_b32_e32 v1, 3, v16
	v_ashrrev_i32_e32 v0, 3, v16
	v_lshlrev_b32_e32 v10, 2, v17
	v_mul_lo_u32 v11, v18, s86
	v_and_b32_e32 v12, 56, v1
	v_lshlrev_b32_e32 v13, 2, v0
	v_add3_u32 v10, 0, v10, v11
	v_mul_u32_u24_e32 v11, 0x104, v12
	s_and_b32 s0, s2, 0x7fffffc0
	v_add3_u32 v11, 0, v13, v11
	v_add_u32_e32 v0, s0, v0
	v_lshlrev_b32_e32 v148, 1, v12
	v_add_u32_e32 v12, 0x400, v11
	v_ashrrev_i32_e32 v1, 31, v0
	v_readlane_b32 s0, v253, 30
	v_lshlrev_b64 v[0:1], 12, v[0:1]
	v_readlane_b32 s1, v253, 31
	s_lshl_b32 s72, s3, 1
	s_waitcnt vmcnt(15)
	ds_write_b32 v10, v2
	s_waitcnt vmcnt(14)
	ds_write_b32 v10, v3 offset:2080
	s_waitcnt vmcnt(13)
	ds_write_b32 v10, v4 offset:4160
	s_waitcnt vmcnt(12)
	ds_write_b32 v10, v5 offset:6240
	s_waitcnt vmcnt(11)
	ds_write_b32 v10, v6 offset:8320
	s_waitcnt vmcnt(10)
	ds_write_b32 v10, v7 offset:10400
	s_waitcnt vmcnt(9)
	ds_write_b32 v10, v8 offset:12480
	s_waitcnt vmcnt(8)
	ds_write_b32 v10, v9 offset:14560
	s_waitcnt lgkmcnt(0)
	s_barrier
	ds_read2_b32 v[2:3], v11 offset1:65
	ds_read2_b32 v[4:5], v11 offset0:130 offset1:195
	ds_read2_b32 v[6:7], v12 offset0:4 offset1:69
	ds_read2_b32 v[8:9], v12 offset0:134 offset1:199
	v_lshl_add_u64 v[0:1], s[0:1], 0, v[0:1]
	v_lshl_add_u64 v[0:1], v[0:1], 0, s[72:73]
	v_lshl_add_u64 v[10:11], v[0:1], 0, v[148:149]
	s_waitcnt lgkmcnt(3)
	v_cvt_pk_bf16_f32 v0, v2, v3
	s_waitcnt lgkmcnt(2)
	v_cvt_pk_bf16_f32 v1, v4, v5
	s_waitcnt lgkmcnt(1)
	v_cvt_pk_bf16_f32 v2, v6, v7
	s_waitcnt lgkmcnt(0)
	v_cvt_pk_bf16_f32 v3, v8, v9
	global_store_dwordx4 v[10:11], v[0:3], off
	s_barrier

; DEVI int srccol_ffn(int n) { return ((n >> 7) & 1) * FFN_H + (n >> 8) * 128 + (n & 127); }
; DEVI void conv_tile(unsigned char* smem, const float* src, int ldsrc, int K, bf16_t* dst, int mode, int ntile, int ktile) {
;     ...
;     const int n = n0 + tx;
;     const int sc = mode == 0 ? srccol_win(n) : (mode == 1 ? srccol_ffn(n) : n);
; #pragma unroll
;     for (int i = 0; i < 8; ++i) {
;         const int kk = ty + 8 * i;
;         tile[kk * 65 + tx] = sc >= 0 ? src[(size_t)(k0 + kk) * ldsrc + sc] : 0.0f;
.LBB0_147:
	s_andn2_b64 vcc, exec, s[0:1]
	s_cbranch_vccnz .LBB0_149
	v_mov_b32_e32 v18, v199
	s_and_b32 s1, s14, 0x7c0
	v_ashrrev_i32_e32 v20, 6, v18
	s_and_b32 s0, s13, 0x7fc0
	v_add_u32_e32 v2, s1, v20
	v_and_b32_e32 v19, 63, v18
	s_addk_i32 s0, 0xbb00
	v_readlane_b32 s2, v254, 0
	v_ashrrev_i32_e32 v3, 31, v2
	v_add_u32_e32 v6, 8, v2
	v_add_u32_e32 v8, 16, v2
	v_or_b32_e32 v148, s0, v19
	v_readlane_b32 s3, v254, 1
	v_lshlrev_b64 v[4:5], 13, v[2:3]
	v_ashrrev_i32_e32 v7, 31, v6
	v_ashrrev_i32_e32 v9, 31, v8
	v_add_u32_e32 v10, 24, v2
	v_add_u32_e32 v12, 32, v2
	v_add_u32_e32 v14, 40, v2
	v_add_u32_e32 v16, 48, v2
	v_add_u32_e32 v2, 56, v2
	v_lshl_add_u64 v[0:1], v[148:149], 2, s[2:3]
	v_lshlrev_b64 v[6:7], 13, v[6:7]
	v_lshlrev_b64 v[8:9], 13, v[8:9]
	v_ashrrev_i32_e32 v11, 31, v10
	v_ashrrev_i32_e32 v13, 31, v12
	v_ashrrev_i32_e32 v15, 31, v14
	v_ashrrev_i32_e32 v17, 31, v16
	v_ashrrev_i32_e32 v3, 31, v2
	v_lshl_add_u64 v[4:5], v[0:1], 0, v[4:5]
	v_lshl_add_u64 v[6:7], v[0:1], 0, v[6:7]
	v_lshl_add_u64 v[8:9], v[0:1], 0, v[8:9]
	v_lshlrev_b64 v[10:11], 13, v[10:11]
	v_lshlrev_b64 v[12:13], 13, v[12:13]
	v_lshlrev_b64 v[14:15], 13, v[14:15]
	v_lshlrev_b64 v[16:17], 13, v[16:17]
	v_lshlrev_b64 v[2:3], 13, v[2:3]
	v_lshl_add_u64 v[10:11], v[0:1], 0, v[10:11]
	v_lshl_add_u64 v[12:13], v[0:1], 0, v[12:13]
	v_lshl_add_u64 v[14:15], v[0:1], 0, v[14:15]
	v_lshl_add_u64 v[16:17], v[0:1], 0, v[16:17]
	v_lshl_add_u64 v[0:1], v[0:1], 0, v[2:3]
	v_mov_b64_e32 v[228:229], v[4:5]
	v_mov_b64_e32 v[230:231], v[6:7]
	v_mov_b64_e32 v[232:233], v[8:9]
	v_mov_b64_e32 v[234:235], v[10:11]
	v_mov_b64_e32 v[236:237], v[12:13]
	v_mov_b64_e32 v[238:239], v[14:15]
	v_mov_b64_e32 v[240:241], v[16:17]
	v_mov_b64_e32 v[242:243], v[0:1]
	global_load_dword v2, v[4:5], off
	global_load_dword v3, v[6:7], off
	s_nop 0
	global_load_dword v4, v[8:9], off
	global_load_dword v5, v[10:11], off
	global_load_dword v6, v[12:13], off
	global_load_dword v7, v[14:15], off
	s_nop 0
	global_load_dword v8, v[16:17], off
	global_load_dword v9, v[0:1], off
	s_add_i32 s101, s15, s90
	s_cmp_lt_u32 s101, 0x2680
	s_cbranch_scc0 .Lcvt_nt_woutB
	global_load_dword v244, v[228:229], off offset:2048
	global_load_dword v244, v[230:231], off offset:2048
	global_load_dword v244, v[232:233], off offset:2048
	global_load_dword v244, v[234:235], off offset:2048
	global_load_dword v244, v[236:237], off offset:2048
	global_load_dword v244, v[238:239], off offset:2048
	global_load_dword v244, v[240:241], off offset:2048
	global_load_dword v244, v[242:243], off offset:2048
	s_branch .Lcvt_j_woutB

; DEVI void conv_tile(unsigned char* smem, const float* src, int ldsrc, int K, bf16_t* dst, int mode, int ntile, int ktile) {
;     ...
;         tile[kk * 65 + tx] = sc >= 0 ? src[(size_t)(k0 + kk) * ldsrc + sc] : 0.0f;
;     }
;     __syncthreads();
;     const int nr = tid >> 3, ks = (tid & 7) * 8;
;     float v[8];
; #pragma unroll
;     for (int j = 0; j < 8; ++j) v[j] = tile[(ks + j) * 65 + nr];
;     u32x4 w; w.x = cvt_pk_bf16(v[0], v[1]); w.y = cvt_pk_bf16(v[2], v[3]); w.z = cvt_pk_bf16(v[4], v[5]); w.w = cvt_pk_bf16(v[6], v[7]);
;     *(u32x4*)(dst + (size_t)(n0 + nr) * K + k0 + ks) = w;
;     __syncthreads();
.Lcvt_j_woutB:
	v_lshlrev_b32_e32 v1, 3, v18
	v_ashrrev_i32_e32 v0, 3, v18
	v_lshlrev_b32_e32 v10, 2, v19
	v_mul_lo_u32 v11, v20, s86
	v_and_b32_e32 v12, 56, v1
	v_lshlrev_b32_e32 v13, 2, v0
	v_add3_u32 v10, 0, v10, v11
	v_mul_u32_u24_e32 v11, 0x104, v12
	v_add3_u32 v11, 0, v13, v11
	v_add_u32_e32 v0, s0, v0
	v_lshlrev_b32_e32 v148, 1, v12
	v_add_u32_e32 v12, 0x400, v11
	s_lshl_b32 s72, s1, 1
	v_ashrrev_i32_e32 v1, 31, v0
	v_readlane_b32 s0, v253, 32
	v_lshlrev_b64 v[0:1], 12, v[0:1]
	v_readlane_b32 s1, v253, 33
	s_waitcnt vmcnt(15)
	ds_write_b32 v10, v2
	s_waitcnt vmcnt(14)
	ds_write_b32 v10, v3 offset:2080
	s_waitcnt vmcnt(13)
	ds_write_b32 v10, v4 offset:4160
	s_waitcnt vmcnt(12)
	ds_write_b32 v10, v5 offset:6240
	s_waitcnt vmcnt(11)
	ds_write_b32 v10, v6 offset:8320
	s_waitcnt vmcnt(10)
	ds_write_b32 v10, v7 offset:10400
	s_waitcnt vmcnt(9)
	ds_write_b32 v10, v8 offset:12480
	s_waitcnt vmcnt(8)
	ds_write_b32 v10, v9 offset:14560
	s_waitcnt lgkmcnt(0)
	s_barrier
	ds_read2_b32 v[2:3], v11 offset1:65
	ds_read2_b32 v[4:5], v11 offset0:130 offset1:195
	ds_read2_b32 v[6:7], v12 offset0:4 offset1:69
	ds_read2_b32 v[8:9], v12 offset0:134 offset1:199
	v_lshl_add_u64 v[0:1], s[0:1], 0, v[0:1]
	v_lshl_add_u64 v[0:1], v[0:1], 0, s[72:73]
	v_lshl_add_u64 v[10:11], v[0:1], 0, v[148:149]
	s_waitcnt lgkmcnt(3)
	v_cvt_pk_bf16_f32 v0, v2, v3
	s_waitcnt lgkmcnt(2)
	v_cvt_pk_bf16_f32 v1, v4, v5
	s_waitcnt lgkmcnt(1)
	v_cvt_pk_bf16_f32 v2, v6, v7
	s_waitcnt lgkmcnt(0)
	v_cvt_pk_bf16_f32 v3, v8, v9
	global_store_dwordx4 v[10:11], v[0:3], off
	s_barrier
